# relative-position bias table (layer independent) built only in layer 0 of each launch instead of in every layer
# speedup vs baseline: 1.0070x; 1.0070x over previous
; #define TIDX tid_opaque()
; __device__ void convert_phase(unsigned char* smem, const Params& p, int l) {
;     ...
;     if (blockIdx.x == 1 % gridDim.x) {
;         const float* rb = ((const float*)ldp(18));
;         for (int i = TIDX; i < 24 * 129; i += 512) { const int hh = i / 129, delta = i % 129 - 64, d = 1 << (2 * (hh >> 3)); const int rel = delta * d;
;             const int n = rel < 0 ? -rel : rel; int bucket = rel > 0 ? 16 : 0;
;             if (n < 8) bucket += n; else { const float nf = (float)n; int lg = 8 + (int)(logf(nf / 8.0f) / 4.852030263919617f * 8.0f); if (lg > 15) lg = 15; bucket += lg; }
;             sm[1024 + i] = rb[bucket * 24 + hh]; }
.LBB0_372:
	s_cmp_lg_u32 s5, 1
	s_cselect_b64 s[6:7], -1, 0
	v_cndmask_b32_e64 v0, 0, 1, s[6:7]
	v_cmp_ne_u32_e32 vcc, s2, v0
	s_cbranch_vccnz .LBB0_381
	s_cmp_gt_u32 s90, 19
	s_cbranch_scc1 .LBB0_381
	s_add_i32 s6, 0, 0x23e90
	s_cmp_lg_u32 s6, -1
	s_cselect_b32 s6, s6, 0
	s_cselect_b32 s7, s41, 0
	v_mov_b32_e32 v0, s6
	v_mov_b32_e32 v1, s7
	ds_read_b64 v[2:3], v0
	s_waitcnt vmcnt(0) lgkmcnt(0)
	v_mov_b32_e32 v0, v234
	s_movk_i32 s8, 0xc18
	s_waitcnt lgkmcnt(0)
	v_readfirstlane_b32 s7, v3
	v_readfirstlane_b32 s6, v2
	v_cmp_gt_i32_e32 vcc, s8, v0
	s_and_saveexec_b64 s[8:9], vcc
	s_cbranch_execz .LBB0_380
	v_ashrrev_i32_e32 v1, 31, v0
	v_lshl_add_u64 v[2:3], v[0:1], 2, s[0:1]
	s_mov_b64 s[0:1], 0x22c01000
	v_lshl_add_u64 v[2:3], v[2:3], 0, s[0:1]
	s_mov_b64 s[0:1], 0
	s_branch .LBB0_376
